# fnpipe: software-pipelined final RMSNorm row loop (next row's loads in flight, counted vmcnt, stores not drained per chunk); on top of v83
# speedup vs baseline: 1.0098x; 1.0024x over previous
; #define GAS __attribute__((address_space(1)))
; __device__ __forceinline__ float bf_lo(unsigned w) { return __uint_as_float(w << 16); }
; __device__ __forceinline__ float bf_hi(unsigned w) { return __uint_as_float(w & 0xffff0000u); }
; __device__ __forceinline__ int lane_id_opaque() { int l; asm volatile("v_mbcnt_lo_u32_b32 %0, -1, 0\n\tv_mbcnt_hi_u32_b32 %0, -1, %0" : "=&v"(l)); return l; }
; __global__ void __launch_bounds__(NTHREADS, 2) __attribute__((amdgpu_waves_per_eu(2, 2))) hymba_fwd(Params p) {
;     ...
;     {
;         int tidf = wave_s * 64 + lane_id_opaque(); asm volatile("" : "+v"(tidf));
;         const int tid = tidf, lane = tid & 63, wave = tid >> 6;
;         const int gw = vcu * 8 + wave, NGW = G * 8;
;         f32x4 gf[4][2];
; #pragma unroll
;         for (int j = 0; j < 4; ++j) { gf[j][0] = ((const GAS f32x4*)p.final_norm)[2 * (lane + 64 * j)]; gf[j][1] = ((const GAS f32x4*)p.final_norm)[2 * (lane + 64 * j) + 1]; }
;         for (int row = gw; row < T_TOK; row += NGW) {
;             const GAS u32x4* yr = (const GAS u32x4*)((const GAS bf16_t*)(ws + WS_XN) + (size_t)row * 2048);
;             GAS f32x4* orow = (GAS f32x4*)((GAS float*)p.out + (size_t)row * 2048);
;             const float rs = rsqrtf(((const GAS float*)SSF)[row] * (1.0f / 2048.0f) + EPS);
; #pragma unroll
;             for (int j = 0; j < 4; ++j) {
;                 const u32x4 w = yr[lane + 64 * j];
;                 orow[2 * (lane + 64 * j)] = (f32x4){bf_lo(w.x), bf_hi(w.x), bf_lo(w.y), bf_hi(w.y)} * rs * gf[j][0];
;                 orow[2 * (lane + 64 * j) + 1] = (f32x4){bf_lo(w.z), bf_hi(w.z), bf_lo(w.w), bf_hi(w.w)} * rs * gf[j][1];
;             }
;         }
.LBB0_772:
	v_mbcnt_lo_u32_b32 v0, -1, 0
	v_mbcnt_hi_u32_b32 v0, -1, v0
	v_readlane_b32 s0, v254, 0
	v_add_u32_e32 v0, s81, v0
	s_lshl_b32 s2, s0, 3
	v_ashrrev_i32_e32 v32, 6, v0
	v_add_u32_e32 v38, s2, v32
	s_mov_b32 s0, 0x8000
	v_cmp_gt_i32_e32 vcc, s0, v38
	s_and_saveexec_b64 s[0:1], vcc
	s_cbranch_execz .LBB0_775
	v_readlane_b32 s4, v254, 8
	v_and_b32_e32 v39, 63, v0
	v_readlane_b32 s12, v254, 16
	v_readlane_b32 s13, v254, 17
	v_readlane_b32 s14, v254, 18
	v_readlane_b32 s15, v254, 19
	v_readlane_b32 s16, v254, 20
	v_readlane_b32 s17, v254, 21
	v_lshlrev_b32_e32 v36, 5, v39
	v_mov_b32_e32 v37, 0
	v_readlane_b32 s18, v254, 22
	v_readlane_b32 s19, v254, 23
	s_mov_b64 s[12:13], s[16:17]
	v_lshl_add_u64 v[24:25], s[12:13], 0, v[36:37]
	s_mov_b64 s[0:1], 0x1000
	v_lshl_add_u64 v[26:27], v[24:25], 0, s[0:1]
	s_movk_i32 s0, 0x1000
	global_load_dwordx4 v[0:3], v36, s[12:13] offset:16
	global_load_dwordx4 v[4:7], v36, s[12:13]
	global_load_dwordx4 v[8:11], v36, s[12:13] offset:2064
	global_load_dwordx4 v[12:15], v36, s[12:13] offset:2048
	v_add_co_u32_e32 v34, vcc, s0, v24
	s_mov_b64 s[0:1], 0x1800
	s_nop 0
	v_addc_co_u32_e32 v35, vcc, 0, v25, vcc
	global_load_dwordx4 v[16:19], v[34:35], off
	global_load_dwordx4 v[20:23], v[26:27], off offset:16
	v_lshl_add_u64 v[40:41], v[24:25], 0, s[0:1]
	global_load_dwordx4 v[24:27], v[34:35], off offset:2048
	global_load_dwordx4 v[28:31], v[40:41], off offset:16
	v_ashrrev_i32_e32 v33, 31, v32
	s_ashr_i32 s3, s2, 31
	v_lshl_add_u64 v[40:41], v[32:33], 0, s[2:3]
	v_lshl_add_u64 v[32:33], v[40:41], 2, s[38:39]
	v_lshlrev_b64 v[34:35], 12, v[40:41]
	v_lshlrev_b64 v[40:41], 13, v[40:41]
	v_readlane_b32 s5, v254, 9
	v_readlane_b32 s6, v254, 10
	v_readlane_b32 s7, v254, 11
	s_mov_b64 s[14:15], s[18:19]
	s_lshl_b32 s0, s70, 3
	v_lshl_or_b32 v34, v39, 4, v34
	v_or_b32_e32 v40, v40, v36
	v_readlane_b32 s8, v254, 12
	v_readlane_b32 s9, v254, 13
	v_readlane_b32 s10, v254, 14
	v_readlane_b32 s11, v254, 15
	s_ashr_i32 s1, s0, 31
	v_lshl_add_u64 v[34:35], s[58:59], 0, v[34:35]
	s_mov_b64 s[4:5], 0xc00
	v_lshl_add_u64 v[36:37], s[14:15], 0, v[40:41]
	s_mov_b64 s[6:7], 0x1810
	s_lshl_b64 s[2:3], s[0:1], 2
	v_lshl_add_u64 v[34:35], v[34:35], 0, s[4:5]
	s_lshl_b64 s[4:5], s[0:1], 12
	v_lshl_add_u64 v[36:37], v[36:37], 0, s[6:7]
	s_lshl_b64 s[6:7], s[0:1], 13
	s_mov_b64 s[8:9], 0
	v_mov_b32_e32 v39, 0x358637bd
	s_mov_b32 s1, 0x800000
	s_movk_i32 s10, 0xf000
	s_movk_i32 s11, 0x7fff
	v_add_co_u32_e32 v58, vcc, 0xfffff000, v36
	s_nop 1
	v_addc_co_u32_e32 v59, vcc, -1, v37, vcc
	s_mov_b32 s13, 8
	global_load_dword v56, v[32:33], off
	global_load_dwordx4 v[40:43], v[34:35], off offset:-3072
	global_load_dwordx4 v[44:47], v[34:35], off offset:-2048
	global_load_dwordx4 v[48:51], v[34:35], off offset:-1024
	global_load_dwordx4 v[52:55], v[34:35], off offset:0
	v_lshl_add_u64 v[32:33], v[32:33], 0, s[2:3]
	v_lshl_add_u64 v[34:35], v[34:35], 0, s[4:5]
.Lfn_loop:
	global_load_dword v76, v[32:33], off
	global_load_dwordx4 v[60:63], v[34:35], off offset:-3072
	global_load_dwordx4 v[64:67], v[34:35], off offset:-2048
	global_load_dwordx4 v[68:71], v[34:35], off offset:-1024
	global_load_dwordx4 v[72:75], v[34:35], off offset:0
	v_lshl_add_u64 v[32:33], v[32:33], 0, s[2:3]
	v_lshl_add_u64 v[34:35], v[34:35], 0, s[4:5]
	s_cmp_eq_u32 s13, 8
	s_cbranch_scc1 .Lfn_first
	s_waitcnt vmcnt(13)
	s_branch .Lfn_goA
.Lfn_first:
	s_waitcnt vmcnt(5)
.Lfn_goA:
	v_fmamk_f32 v78, v56, 0x3a000000, v39
	v_rsq_f32_e32 v78, v78
	v_lshlrev_b32_e32 v80, 16, v40
	v_and_b32_e32 v81, 0xffff0000, v40
	v_lshlrev_b32_e32 v82, 16, v41
	v_and_b32_e32 v83, 0xffff0000, v41
	v_lshlrev_b32_e32 v84, 16, v42
	v_and_b32_e32 v85, 0xffff0000, v42
	v_lshlrev_b32_e32 v86, 16, v43
	v_and_b32_e32 v87, 0xffff0000, v43
	v_pk_mul_f32 v[80:81], v[78:79], v[80:81] op_sel_hi:[0,1]
	v_pk_mul_f32 v[82:83], v[78:79], v[82:83] op_sel_hi:[0,1]
	v_pk_mul_f32 v[84:85], v[78:79], v[84:85] op_sel_hi:[0,1]
	v_pk_mul_f32 v[86:87], v[78:79], v[86:87] op_sel_hi:[0,1]
	v_pk_mul_f32 v[80:81], v[4:5], v[80:81]
	v_pk_mul_f32 v[82:83], v[6:7], v[82:83]
	v_pk_mul_f32 v[84:85], v[0:1], v[84:85]
	v_pk_mul_f32 v[86:87], v[2:3], v[86:87]
	global_store_dwordx4 v[58:59], v[80:83], off offset:-2064
	global_store_dwordx4 v[58:59], v[84:87], off offset:-2048
	v_lshlrev_b32_e32 v96, 16, v44
	v_and_b32_e32 v97, 0xffff0000, v44
	v_lshlrev_b32_e32 v98, 16, v45
	v_and_b32_e32 v99, 0xffff0000, v45
	v_lshlrev_b32_e32 v100, 16, v46
	v_and_b32_e32 v101, 0xffff0000, v46
	v_lshlrev_b32_e32 v102, 16, v47
	v_and_b32_e32 v103, 0xffff0000, v47
	v_pk_mul_f32 v[96:97], v[78:79], v[96:97] op_sel_hi:[0,1]
	v_pk_mul_f32 v[98:99], v[78:79], v[98:99] op_sel_hi:[0,1]
	v_pk_mul_f32 v[100:101], v[78:79], v[100:101] op_sel_hi:[0,1]
	v_pk_mul_f32 v[102:103], v[78:79], v[102:103] op_sel_hi:[0,1]
	v_pk_mul_f32 v[96:97], v[12:13], v[96:97]
	v_pk_mul_f32 v[98:99], v[14:15], v[98:99]
	v_pk_mul_f32 v[100:101], v[8:9], v[100:101]
	v_pk_mul_f32 v[102:103], v[10:11], v[102:103]
	global_store_dwordx4 v[58:59], v[96:99], off offset:-16
	global_store_dwordx4 v[36:37], v[100:103], off offset:-4096
	v_lshlrev_b32_e32 v80, 16, v48
	v_and_b32_e32 v81, 0xffff0000, v48
	v_lshlrev_b32_e32 v82, 16, v49
	v_and_b32_e32 v83, 0xffff0000, v49
	v_lshlrev_b32_e32 v84, 16, v50
	v_and_b32_e32 v85, 0xffff0000, v50
	v_lshlrev_b32_e32 v86, 16, v51
	v_and_b32_e32 v87, 0xffff0000, v51
	v_pk_mul_f32 v[80:81], v[78:79], v[80:81] op_sel_hi:[0,1]
	v_pk_mul_f32 v[82:83], v[78:79], v[82:83] op_sel_hi:[0,1]
	v_pk_mul_f32 v[84:85], v[78:79], v[84:85] op_sel_hi:[0,1]
	v_pk_mul_f32 v[86:87], v[78:79], v[86:87] op_sel_hi:[0,1]
	v_pk_mul_f32 v[80:81], v[16:17], v[80:81]
	v_pk_mul_f32 v[82:83], v[18:19], v[82:83]
	v_pk_mul_f32 v[84:85], v[20:21], v[84:85]
	v_pk_mul_f32 v[86:87], v[22:23], v[86:87]
	global_store_dwordx4 v[36:37], v[80:83], off offset:-2064
	global_store_dwordx4 v[36:37], v[84:87], off offset:-2048
	v_lshlrev_b32_e32 v96, 16, v52
	v_and_b32_e32 v97, 0xffff0000, v52
	v_lshlrev_b32_e32 v98, 16, v53
	v_and_b32_e32 v99, 0xffff0000, v53
	v_lshlrev_b32_e32 v100, 16, v54
	v_and_b32_e32 v101, 0xffff0000, v54
	v_lshlrev_b32_e32 v102, 16, v55
	v_and_b32_e32 v103, 0xffff0000, v55
	v_pk_mul_f32 v[96:97], v[78:79], v[96:97] op_sel_hi:[0,1]
	v_pk_mul_f32 v[98:99], v[78:79], v[98:99] op_sel_hi:[0,1]
	v_pk_mul_f32 v[100:101], v[78:79], v[100:101] op_sel_hi:[0,1]
	v_pk_mul_f32 v[102:103], v[78:79], v[102:103] op_sel_hi:[0,1]
	v_pk_mul_f32 v[96:97], v[24:25], v[96:97]
	v_pk_mul_f32 v[98:99], v[26:27], v[98:99]
	v_pk_mul_f32 v[100:101], v[28:29], v[100:101]
	v_pk_mul_f32 v[102:103], v[30:31], v[102:103]
	global_store_dwordx4 v[36:37], v[96:99], off offset:-16
	global_store_dwordx4 v[36:37], v[100:103], off
	v_lshl_add_u64 v[36:37], v[36:37], 0, s[6:7]
	v_lshl_add_u64 v[58:59], v[58:59], 0, s[6:7]
	s_cmp_eq_u32 s13, 1
	s_cbranch_scc1 .Lfn_last
; #define GAS __attribute__((address_space(1)))
; __device__ __forceinline__ float bf_lo(unsigned w) { return __uint_as_float(w << 16); }
; __device__ __forceinline__ float bf_hi(unsigned w) { return __uint_as_float(w & 0xffff0000u); }
; __global__ void __launch_bounds__(NTHREADS, 2) __attribute__((amdgpu_waves_per_eu(2, 2))) hymba_fwd(Params p) {
;     ...
;         for (int row = gw; row < T_TOK; row += NGW) {
;             const GAS u32x4* yr = (const GAS u32x4*)((const GAS bf16_t*)(ws + WS_XN) + (size_t)row * 2048);
;             GAS f32x4* orow = (GAS f32x4*)((GAS float*)p.out + (size_t)row * 2048);
;             const float rs = rsqrtf(((const GAS float*)SSF)[row] * (1.0f / 2048.0f) + EPS);
; #pragma unroll
;             for (int j = 0; j < 4; ++j) {
;                 const u32x4 w = yr[lane + 64 * j];
;                 orow[2 * (lane + 64 * j)] = (f32x4){bf_lo(w.x), bf_hi(w.x), bf_lo(w.y), bf_hi(w.y)} * rs * gf[j][0];
;                 orow[2 * (lane + 64 * j) + 1] = (f32x4){bf_lo(w.z), bf_hi(w.z), bf_lo(w.w), bf_hi(w.w)} * rs * gf[j][1];
;             }
	global_load_dword v56, v[32:33], off
	global_load_dwordx4 v[40:43], v[34:35], off offset:-3072
	global_load_dwordx4 v[44:47], v[34:35], off offset:-2048
	global_load_dwordx4 v[48:51], v[34:35], off offset:-1024
	global_load_dwordx4 v[52:55], v[34:35], off offset:0
	v_lshl_add_u64 v[32:33], v[32:33], 0, s[2:3]
	v_lshl_add_u64 v[34:35], v[34:35], 0, s[4:5]
	s_waitcnt vmcnt(13)
	v_fmamk_f32 v78, v76, 0x3a000000, v39
	v_rsq_f32_e32 v78, v78
	v_lshlrev_b32_e32 v80, 16, v60
	v_and_b32_e32 v81, 0xffff0000, v60
	v_lshlrev_b32_e32 v82, 16, v61
	v_and_b32_e32 v83, 0xffff0000, v61
	v_lshlrev_b32_e32 v84, 16, v62
	v_and_b32_e32 v85, 0xffff0000, v62
	v_lshlrev_b32_e32 v86, 16, v63
	v_and_b32_e32 v87, 0xffff0000, v63
	v_pk_mul_f32 v[80:81], v[78:79], v[80:81] op_sel_hi:[0,1]
	v_pk_mul_f32 v[82:83], v[78:79], v[82:83] op_sel_hi:[0,1]
	v_pk_mul_f32 v[84:85], v[78:79], v[84:85] op_sel_hi:[0,1]
	v_pk_mul_f32 v[86:87], v[78:79], v[86:87] op_sel_hi:[0,1]
	v_pk_mul_f32 v[80:81], v[4:5], v[80:81]
	v_pk_mul_f32 v[82:83], v[6:7], v[82:83]
	v_pk_mul_f32 v[84:85], v[0:1], v[84:85]
	v_pk_mul_f32 v[86:87], v[2:3], v[86:87]
	global_store_dwordx4 v[58:59], v[80:83], off offset:-2064
	global_store_dwordx4 v[58:59], v[84:87], off offset:-2048
	v_lshlrev_b32_e32 v96, 16, v64
	v_and_b32_e32 v97, 0xffff0000, v64
	v_lshlrev_b32_e32 v98, 16, v65
	v_and_b32_e32 v99, 0xffff0000, v65
	v_lshlrev_b32_e32 v100, 16, v66
	v_and_b32_e32 v101, 0xffff0000, v66
	v_lshlrev_b32_e32 v102, 16, v67
	v_and_b32_e32 v103, 0xffff0000, v67
	v_pk_mul_f32 v[96:97], v[78:79], v[96:97] op_sel_hi:[0,1]
	v_pk_mul_f32 v[98:99], v[78:79], v[98:99] op_sel_hi:[0,1]
	v_pk_mul_f32 v[100:101], v[78:79], v[100:101] op_sel_hi:[0,1]
	v_pk_mul_f32 v[102:103], v[78:79], v[102:103] op_sel_hi:[0,1]
	v_pk_mul_f32 v[96:97], v[12:13], v[96:97]
	v_pk_mul_f32 v[98:99], v[14:15], v[98:99]
	v_pk_mul_f32 v[100:101], v[8:9], v[100:101]
	v_pk_mul_f32 v[102:103], v[10:11], v[102:103]
	global_store_dwordx4 v[58:59], v[96:99], off offset:-16
	global_store_dwordx4 v[36:37], v[100:103], off offset:-4096
	v_lshlrev_b32_e32 v80, 16, v68
	v_and_b32_e32 v81, 0xffff0000, v68
	v_lshlrev_b32_e32 v82, 16, v69
	v_and_b32_e32 v83, 0xffff0000, v69
	v_lshlrev_b32_e32 v84, 16, v70
	v_and_b32_e32 v85, 0xffff0000, v70
	v_lshlrev_b32_e32 v86, 16, v71
	v_and_b32_e32 v87, 0xffff0000, v71
	v_pk_mul_f32 v[80:81], v[78:79], v[80:81] op_sel_hi:[0,1]
	v_pk_mul_f32 v[82:83], v[78:79], v[82:83] op_sel_hi:[0,1]
	v_pk_mul_f32 v[84:85], v[78:79], v[84:85] op_sel_hi:[0,1]
	v_pk_mul_f32 v[86:87], v[78:79], v[86:87] op_sel_hi:[0,1]
	v_pk_mul_f32 v[80:81], v[16:17], v[80:81]
	v_pk_mul_f32 v[82:83], v[18:19], v[82:83]
	v_pk_mul_f32 v[84:85], v[20:21], v[84:85]
	v_pk_mul_f32 v[86:87], v[22:23], v[86:87]
	global_store_dwordx4 v[36:37], v[80:83], off offset:-2064
	global_store_dwordx4 v[36:37], v[84:87], off offset:-2048
	v_lshlrev_b32_e32 v96, 16, v72
	v_and_b32_e32 v97, 0xffff0000, v72
	v_lshlrev_b32_e32 v98, 16, v73
	v_and_b32_e32 v99, 0xffff0000, v73
	v_lshlrev_b32_e32 v100, 16, v74
	v_and_b32_e32 v101, 0xffff0000, v74
	v_lshlrev_b32_e32 v102, 16, v75
	v_and_b32_e32 v103, 0xffff0000, v75
	v_pk_mul_f32 v[96:97], v[78:79], v[96:97] op_sel_hi:[0,1]
	v_pk_mul_f32 v[98:99], v[78:79], v[98:99] op_sel_hi:[0,1]
	v_pk_mul_f32 v[100:101], v[78:79], v[100:101] op_sel_hi:[0,1]
	v_pk_mul_f32 v[102:103], v[78:79], v[102:103] op_sel_hi:[0,1]
	v_pk_mul_f32 v[96:97], v[24:25], v[96:97]
	v_pk_mul_f32 v[98:99], v[26:27], v[98:99]
	v_pk_mul_f32 v[100:101], v[28:29], v[100:101]
	v_pk_mul_f32 v[102:103], v[30:31], v[102:103]
	global_store_dwordx4 v[36:37], v[96:99], off offset:-16
	global_store_dwordx4 v[36:37], v[100:103], off
	v_lshl_add_u64 v[36:37], v[36:37], 0, s[6:7]
	v_lshl_add_u64 v[58:59], v[58:59], 0, s[6:7]
	s_sub_u32 s13, s13, 1
	s_branch .Lfn_loop
; __device__ __forceinline__ float bf_lo(unsigned w) { return __uint_as_float(w << 16); }
; __device__ __forceinline__ float bf_hi(unsigned w) { return __uint_as_float(w & 0xffff0000u); }
; __global__ void __launch_bounds__(NTHREADS, 2) __attribute__((amdgpu_waves_per_eu(2, 2))) hymba_fwd(Params p) {
;     ...
;             for (int j = 0; j < 4; ++j) {
;                 const u32x4 w = yr[lane + 64 * j];
;                 orow[2 * (lane + 64 * j)] = (f32x4){bf_lo(w.x), bf_hi(w.x), bf_lo(w.y), bf_hi(w.y)} * rs * gf[j][0];
;                 orow[2 * (lane + 64 * j) + 1] = (f32x4){bf_lo(w.z), bf_hi(w.z), bf_lo(w.w), bf_hi(w.w)} * rs * gf[j][1];
;             }
.Lfn_last:
	s_waitcnt vmcnt(8)
	v_fmamk_f32 v78, v76, 0x3a000000, v39
	v_rsq_f32_e32 v78, v78
	v_lshlrev_b32_e32 v80, 16, v60
	v_and_b32_e32 v81, 0xffff0000, v60
	v_lshlrev_b32_e32 v82, 16, v61
	v_and_b32_e32 v83, 0xffff0000, v61
	v_lshlrev_b32_e32 v84, 16, v62
	v_and_b32_e32 v85, 0xffff0000, v62
	v_lshlrev_b32_e32 v86, 16, v63
	v_and_b32_e32 v87, 0xffff0000, v63
	v_pk_mul_f32 v[80:81], v[78:79], v[80:81] op_sel_hi:[0,1]
	v_pk_mul_f32 v[82:83], v[78:79], v[82:83] op_sel_hi:[0,1]
	v_pk_mul_f32 v[84:85], v[78:79], v[84:85] op_sel_hi:[0,1]
	v_pk_mul_f32 v[86:87], v[78:79], v[86:87] op_sel_hi:[0,1]
	v_pk_mul_f32 v[80:81], v[4:5], v[80:81]
	v_pk_mul_f32 v[82:83], v[6:7], v[82:83]
	v_pk_mul_f32 v[84:85], v[0:1], v[84:85]
	v_pk_mul_f32 v[86:87], v[2:3], v[86:87]
	global_store_dwordx4 v[58:59], v[80:83], off offset:-2064
	global_store_dwordx4 v[58:59], v[84:87], off offset:-2048
	v_lshlrev_b32_e32 v96, 16, v64
	v_and_b32_e32 v97, 0xffff0000, v64
	v_lshlrev_b32_e32 v98, 16, v65
	v_and_b32_e32 v99, 0xffff0000, v65
	v_lshlrev_b32_e32 v100, 16, v66
	v_and_b32_e32 v101, 0xffff0000, v66
	v_lshlrev_b32_e32 v102, 16, v67
	v_and_b32_e32 v103, 0xffff0000, v67
	v_pk_mul_f32 v[96:97], v[78:79], v[96:97] op_sel_hi:[0,1]
	v_pk_mul_f32 v[98:99], v[78:79], v[98:99] op_sel_hi:[0,1]
	v_pk_mul_f32 v[100:101], v[78:79], v[100:101] op_sel_hi:[0,1]
	v_pk_mul_f32 v[102:103], v[78:79], v[102:103] op_sel_hi:[0,1]
	v_pk_mul_f32 v[96:97], v[12:13], v[96:97]
	v_pk_mul_f32 v[98:99], v[14:15], v[98:99]
	v_pk_mul_f32 v[100:101], v[8:9], v[100:101]
	v_pk_mul_f32 v[102:103], v[10:11], v[102:103]
	global_store_dwordx4 v[58:59], v[96:99], off offset:-16
	global_store_dwordx4 v[36:37], v[100:103], off offset:-4096
	v_lshlrev_b32_e32 v80, 16, v68
	v_and_b32_e32 v81, 0xffff0000, v68
	v_lshlrev_b32_e32 v82, 16, v69
	v_and_b32_e32 v83, 0xffff0000, v69
	v_lshlrev_b32_e32 v84, 16, v70
	v_and_b32_e32 v85, 0xffff0000, v70
	v_lshlrev_b32_e32 v86, 16, v71
	v_and_b32_e32 v87, 0xffff0000, v71
	v_pk_mul_f32 v[80:81], v[78:79], v[80:81] op_sel_hi:[0,1]
	v_pk_mul_f32 v[82:83], v[78:79], v[82:83] op_sel_hi:[0,1]
	v_pk_mul_f32 v[84:85], v[78:79], v[84:85] op_sel_hi:[0,1]
	v_pk_mul_f32 v[86:87], v[78:79], v[86:87] op_sel_hi:[0,1]
	v_pk_mul_f32 v[80:81], v[16:17], v[80:81]
	v_pk_mul_f32 v[82:83], v[18:19], v[82:83]
	v_pk_mul_f32 v[84:85], v[20:21], v[84:85]
	v_pk_mul_f32 v[86:87], v[22:23], v[86:87]
	global_store_dwordx4 v[36:37], v[80:83], off offset:-2064
	global_store_dwordx4 v[36:37], v[84:87], off offset:-2048
	v_lshlrev_b32_e32 v96, 16, v72
	v_and_b32_e32 v97, 0xffff0000, v72
	v_lshlrev_b32_e32 v98, 16, v73
	v_and_b32_e32 v99, 0xffff0000, v73
	v_lshlrev_b32_e32 v100, 16, v74
	v_and_b32_e32 v101, 0xffff0000, v74
	v_lshlrev_b32_e32 v102, 16, v75
	v_and_b32_e32 v103, 0xffff0000, v75
	v_pk_mul_f32 v[96:97], v[78:79], v[96:97] op_sel_hi:[0,1]
	v_pk_mul_f32 v[98:99], v[78:79], v[98:99] op_sel_hi:[0,1]
	v_pk_mul_f32 v[100:101], v[78:79], v[100:101] op_sel_hi:[0,1]
	v_pk_mul_f32 v[102:103], v[78:79], v[102:103] op_sel_hi:[0,1]
	v_pk_mul_f32 v[96:97], v[24:25], v[96:97]
	v_pk_mul_f32 v[98:99], v[26:27], v[98:99]
	v_pk_mul_f32 v[100:101], v[28:29], v[100:101]
	v_pk_mul_f32 v[102:103], v[30:31], v[102:103]
	global_store_dwordx4 v[36:37], v[96:99], off offset:-16
	global_store_dwordx4 v[36:37], v[100:103], off
	v_lshl_add_u64 v[36:37], v[36:37], 0, s[6:7]
	v_lshl_add_u64 v[58:59], v[58:59], 0, s[6:7]
